# scan: o^2 row sums via DPP row rotates instead of 16 ds_bpermute per half-step
# speedup vs baseline: 1.0453x; 1.0017x over previous
; #define LAS __attribute__((address_space(3)))
; __device__ __forceinline__ unsigned cvtpk(float lo, float hi) { return pg8::cvt_pk_bf16(lo, hi); }
; __device__ __forceinline__ bf16x8 cat44(const s16x4 a, const s16x4 b) { return (bf16x8){a[0], a[1], a[2], a[3], b[0], b[1], b[2], b[3]}; }
; __device__ __forceinline__ void scan_mma(f32x4 (&St)[8], const ScanSt& st, f32x4& o, LAS unsigned char* buf, int w, int l16, int g) {
;     const LAS unsigned char* qp = buf + SC_QD + l16 * SC_RS + 8 * g; const LAS unsigned char* kp = buf + SC_KI + l16 * SC_RS + 8 * g;
;     bf16x8 qd[4], ki[4];
; #pragma unroll
;     for (int ks = 0; ks < 4; ++ks) { qd[ks] = cat44(*(const LAS s16x4*)(qp + 64 * ks), *(const LAS s16x4*)(qp + 64 * ks + 32)); ki[ks] = cat44(*(const LAS s16x4*)(kp + 64 * ks), *(const LAS s16x4*)(kp + 64 * ks + 32)); }
;     f32x4 at = {0.f, 0.f, 0.f, 0.f};
; #pragma unroll
;     for (int ks = 0; ks < 4; ++ks) at = __builtin_amdgcn_mfma_f32_16x16x32_bf16(ki[ks], qd[ks], at, 0, 0, 0);
; #pragma unroll
;     for (int i = 0; i < 4; ++i) if (4 * g + i > l16) at[i] = 0.f;
;     const s16x4 pf = __builtin_bit_cast(s16x4, (u32x2){cvtpk(at[0], at[1]), cvtpk(at[2], at[3])});
;     f32x4 oo = {0.f, 0.f, 0.f, 0.f};
; #pragma unroll
;     for (int ks = 0; ks < 4; ++ks) { const f32x4 s0 = St[2 * ks], s1 = St[2 * ks + 1];
;         const bf16x8 sb = __builtin_bit_cast(bf16x8, (u32x4){cvtpk(s0[0], s0[1]), cvtpk(s0[2], s0[3]), cvtpk(s1[0], s1[1]), cvtpk(s1[2], s1[3])});
;         oo = __builtin_amdgcn_mfma_f32_16x16x32_bf16(qd[ks], sb, oo, 0, 0, 0); }
;     oo = __builtin_amdgcn_mfma_f32_16x16x16bf16_1k(pf, st.vf, oo, 0, 0, 0);
; #pragma unroll
;     for (int kt = 0; kt < 8; ++kt) { const s16x4 kst = *(const LAS s16x4*)(buf + SC_KST + (16 * kt + l16) * 32 + 8 * g); const f32x4 d4 = *(const LAS f32x4*)(buf + SC_DEC + (16 * kt + 4 * g) * 4);
;         St[kt] = __builtin_amdgcn_mfma_f32_16x16x16bf16_1k(kst, st.vf, St[kt] * d4, 0, 0, 0); }
;     o = oo;
;     f32x4 q2 = oo * oo;
; #pragma unroll
;     for (int off = 1; off < 16; off <<= 1) { q2[0] += __shfl_xor(q2[0], off); q2[1] += __shfl_xor(q2[1], off); q2[2] += __shfl_xor(q2[2], off); q2[3] += __shfl_xor(q2[3], off); }
;     if (l16 == 0) *(LAS f32x4*)(buf + SC_SSQ + (w * 16 + 4 * g) * 4) = q2;
; }
.LBB0_386:
	s_mov_b64 s[56:57], -1
	s_and_b64 vcc, exec, s[46:47]
	v_add_u32_e32 v177, 0x1000, v156
	v_cvt_pk_bf16_f32 v96, v20, v21
	v_cvt_pk_bf16_f32 v97, v22, v23
	v_cvt_pk_bf16_f32 v98, v28, v29
	v_cvt_pk_bf16_f32 v99, v30, v31
	v_cvt_pk_bf16_f32 v92, v24, v25
	v_cvt_pk_bf16_f32 v93, v26, v27
	v_cvt_pk_bf16_f32 v94, v32, v33
	v_cvt_pk_bf16_f32 v95, v34, v35
	v_cvt_pk_bf16_f32 v88, v36, v37
	v_cvt_pk_bf16_f32 v89, v38, v39
	v_cvt_pk_bf16_f32 v90, v40, v41
	v_cvt_pk_bf16_f32 v91, v42, v43
	v_cvt_pk_bf16_f32 v84, v44, v45
	v_cvt_pk_bf16_f32 v85, v46, v47
	v_cvt_pk_bf16_f32 v86, v48, v49
	v_cvt_pk_bf16_f32 v87, v50, v51
	s_cbranch_vccz .LBB0_400
	ds_read2_b64 v[52:55], v177 offset0:32 offset1:36
	s_waitcnt lgkmcnt(3)
	ds_read2_b64 v[56:59], v156 offset1:4
	ds_read2_b64 v[60:63], v177 offset0:40 offset1:44
	ds_read2_b64 v[64:67], v156 offset0:8 offset1:12
	ds_read2_b64 v[68:71], v177 offset0:48 offset1:52
	v_mov_b32_e32 v0, s43
	s_waitcnt lgkmcnt(3)
	v_mfma_f32_16x16x32_bf16 v[52:55], v[52:55], v[56:59], 0
	s_waitcnt lgkmcnt(1)
	v_mfma_f32_16x16x32_bf16 v[52:55], v[60:63], v[64:67], v[52:55]
	ds_read2_b64 v[60:63], v156 offset0:16 offset1:20
	ds_read2_b64 v[72:75], v156 offset0:24 offset1:28
	ds_read2_b64 v[76:79], v177 offset0:56 offset1:60
	ds_read2st64_b64 v[80:83], v157 offset0:17 offset1:18
	s_waitcnt lgkmcnt(3)
	v_mfma_f32_16x16x32_bf16 v[52:55], v[68:71], v[60:63], v[52:55]
	ds_read_b128 v[68:71], v148 offset:12800
	v_mfma_f32_16x16x32_bf16 v[56:59], v[56:59], v[96:99], 0
	s_waitcnt lgkmcnt(2)
	v_mfma_f32_16x16x32_bf16 v[52:55], v[76:79], v[72:75], v[52:55]
	v_mfma_f32_16x16x32_bf16 v[56:59], v[64:67], v[92:95], v[56:59]
	ds_read_b128 v[64:67], v148 offset:12864
	s_nop 5
	v_cndmask_b32_e64 v0, v52, v0, s[6:7]
	v_cndmask_b32_e64 v2, 0, v53, s[8:9]
	v_cndmask_b32_e64 v3, v54, 0, s[10:11]
	v_cndmask_b32_e64 v53, v55, 0, s[12:13]
	v_cndmask_b32_e64 v0, v0, v52, s[8:9]
	v_cvt_pk_bf16_f32 v3, v3, v53
	v_mfma_f32_16x16x32_bf16 v[52:55], v[60:63], v[88:91], v[56:59]
	v_cvt_pk_bf16_f32 v2, v0, v2
	ds_read_b128 v[60:63], v148 offset:12928
	s_waitcnt lgkmcnt(2)
	v_pk_mul_f32 v[70:71], v[22:23], v[70:71]
	s_waitcnt lgkmcnt(1)
	v_pk_mul_f32 v[58:59], v[30:31], v[66:67]
	v_mfma_f32_16x16x32_bf16 v[52:55], v[72:75], v[84:87], v[52:55]
	v_mul_f32_e64 v56, v28, v64
	v_mul_f32_e64 v57, v29, v65
	ds_read_b128 v[64:67], v148 offset:12992
	ds_read2st64_b64 v[72:75], v157 offset0:19 offset1:20
	v_pk_mul_f32 v[68:69], v[20:21], v[68:69]
	v_mfma_f32_16x16x16_bf16 v[100:103], v[2:3], v[130:131], v[52:55]
	s_waitcnt lgkmcnt(2)
	v_pk_mul_f32 v[62:63], v[26:27], v[62:63]
	s_waitcnt lgkmcnt(1)
	v_pk_mul_f32 v[78:79], v[34:35], v[66:67]
	v_pk_mul_f32 v[76:77], v[32:33], v[64:65]
	v_mfma_f32_16x16x16_bf16 v[52:55], v[80:81], v[130:131], v[68:71]
	v_mul_f32_e64 v60, v24, v60
	v_mul_f32_e64 v61, v25, v61
	ds_read_b128 v[132:135], v148 offset:13120
	ds_read2st64_b64 v[178:181], v157 offset0:23 offset1:24
	v_mfma_f32_16x16x16_bf16 v[64:67], v[82:83], v[130:131], v[56:59]
	ds_read2st64_b64 v[80:83], v157 offset0:21 offset1:22
	ds_read_b128 v[68:71], v148 offset:13056
	s_waitcnt lgkmcnt(4)
	v_mfma_f32_16x16x16_bf16 v[56:59], v[72:73], v[130:131], v[60:63]
	s_waitcnt lgkmcnt(0)
	v_pk_mul_f32 v[70:71], v[38:39], v[70:71]
	v_pk_mul_f32 v[68:69], v[36:37], v[68:69]
	v_mfma_f32_16x16x16_bf16 v[60:63], v[74:75], v[130:131], v[76:79]
	v_mul_f32_e64 v134, v42, v134
	v_mul_f32_e64 v135, v43, v135
	v_pk_mul_f32 v[132:133], v[40:41], v[132:133]
	s_waitcnt lgkmcnt(0)
	v_mfma_f32_16x16x16_bf16 v[72:75], v[80:81], v[130:131], v[68:71]
	ds_read_b128 v[76:79], v148 offset:13184
	ds_read_b128 v[182:185], v148 offset:13248
	s_waitcnt lgkmcnt(1)
	v_pk_mul_f32 v[78:79], v[46:47], v[78:79]
	v_mfma_f32_16x16x16_bf16 v[68:71], v[82:83], v[130:131], v[132:135]
	v_mul_f32_e64 v76, v44, v76
	v_mul_f32_e64 v77, v45, v77
	s_waitcnt lgkmcnt(0)
	s_nop 0
	v_mfma_f32_16x16x16_bf16 v[76:79], v[178:179], v[130:131], v[76:79]
	s_waitcnt lgkmcnt(0)
	s_waitcnt lgkmcnt(0)
	v_pk_mul_f32 v[82:83], v[50:51], v[184:185]
	v_pk_mul_f32 v[80:81], v[48:49], v[182:183]
	s_waitcnt lgkmcnt(0)
	s_waitcnt lgkmcnt(0)
	v_mfma_f32_16x16x16_bf16 v[80:83], v[180:181], v[130:131], v[80:83]
	v_pk_mul_f32 v[132:133], v[100:101], v[100:101]
	v_pk_mul_f32 v[134:135], v[102:103], v[102:103]
	s_nop 1
	v_add_f32_dpp v132, v132, v132 row_ror:1 row_mask:0xf bank_mask:0xf
	v_add_f32_dpp v133, v133, v133 row_ror:1 row_mask:0xf bank_mask:0xf
	v_add_f32_dpp v134, v134, v134 row_ror:1 row_mask:0xf bank_mask:0xf
	v_add_f32_dpp v135, v135, v135 row_ror:1 row_mask:0xf bank_mask:0xf
	v_add_f32_dpp v132, v132, v132 row_ror:2 row_mask:0xf bank_mask:0xf
	v_add_f32_dpp v133, v133, v133 row_ror:2 row_mask:0xf bank_mask:0xf
	v_add_f32_dpp v134, v134, v134 row_ror:2 row_mask:0xf bank_mask:0xf
	v_add_f32_dpp v135, v135, v135 row_ror:2 row_mask:0xf bank_mask:0xf
	v_add_f32_dpp v132, v132, v132 row_ror:4 row_mask:0xf bank_mask:0xf
	v_add_f32_dpp v133, v133, v133 row_ror:4 row_mask:0xf bank_mask:0xf
	v_add_f32_dpp v134, v134, v134 row_ror:4 row_mask:0xf bank_mask:0xf
	v_add_f32_dpp v135, v135, v135 row_ror:4 row_mask:0xf bank_mask:0xf
	v_add_f32_dpp v132, v132, v132 row_ror:8 row_mask:0xf bank_mask:0xf
	v_add_f32_dpp v133, v133, v133 row_ror:8 row_mask:0xf bank_mask:0xf
	v_add_f32_dpp v134, v134, v134 row_ror:8 row_mask:0xf bank_mask:0xf
	v_add_f32_dpp v135, v135, v135 row_ror:8 row_mask:0xf bank_mask:0xf
	s_and_saveexec_b64 s[56:57], s[14:15]
	s_cbranch_execz .LBB0_389
	s_waitcnt lgkmcnt(0)
	v_add_u32_e32 v0, s3, v147
	ds_write_b128 v0, v[132:135] offset:13312
; #define LAS __attribute__((address_space(3)))
; __device__ __forceinline__ float bf2f(unsigned h) { return __uint_as_float(h << 16); }
; __device__ __forceinline__ void scan_gate(const LAS unsigned char* raw, ScanSt& st, LAS unsigned char* buf, float lb, int w, int l16, int g) {
;     ...
;     const LAS unsigned char* e = raw + (4 * g) * 256 + ((2 * w + (l16 >> 3) + 2 * g) & 15) * 16 + (l16 & 7) * 2;
;     unsigned rq[4], rf[4], rv[4], rg[4];
; #pragma unroll
;     for (int j = 0; j < 4; ++j) { rq[j] = *(const LAS unsigned short*)(e + j * 256); rf[j] = *(const LAS unsigned short*)(e + 4096 + j * 256); rv[j] = *(const LAS unsigned short*)(e + 8192 + j * 256); rg[j] = *(const LAS unsigned short*)(e + 12288 + j * 256); }
;     float qv[4], kk[4], cs[4]; float run = 0.f;
; #pragma unroll
;     for (int j = 0; j < 4; ++j) { const float x = bf2f(rf[j]); const float sg = __builtin_amdgcn_rcpf(1.0f + __builtin_amdgcn_exp2f(-x * L2E));
;         const float f = lb + (1.0f - lb) * sg; kk[j] = (1.0f - lb) * (1.0f - sg); run += __builtin_amdgcn_logf(f); cs[j] = run; qv[j] = bf2f(rq[j]); }
;     const float T = run, t1 = __shfl_xor(T, 16), t2 = __shfl_xor(T, 32), t3 = __shfl_xor(t1, 32);
;     const float E = g == 0 ? 0.f : (g == 1 ? t1 : (g == 2 ? (t2 + t3) : (t1 + t2 + t3))), blast = (T + t1) + (t2 + t3);
.LBB0_389:
	s_or_b64 exec, exec, s[56:57]
	s_or_b32 s16, s49, 1
	s_and_b32 s17, s16, 0xff
	s_mulk_i32 s17, 0xab
	s_bfe_u32 s17, s17, 0x70009
	s_mul_i32 s17, s17, 3
	s_sub_i32 s16, s16, s17
	s_and_b32 s16, s16, 0xff
	s_waitcnt lgkmcnt(1)
	v_lshl_add_u32 v132, s16, 14, v142
	ds_read_u16 v2, v132 offset:36864
	ds_read_u16 v3, v132 offset:37120
	s_waitcnt lgkmcnt(3)
	ds_read_u16 v133, v132 offset:37376
	ds_read_u16 v134, v132 offset:37632
	ds_read_u16 v0, v132 offset:33536
	s_waitcnt lgkmcnt(4)
	v_lshlrev_b32_e32 v2, 16, v2
	v_mul_f32_e32 v2, 0xbfb8aa3b, v2
	v_exp_f32_e32 v2, v2
	s_waitcnt lgkmcnt(3)
	v_lshlrev_b32_e32 v3, 16, v3
	v_mul_f32_e32 v3, 0xbfb8aa3b, v3
	s_waitcnt lgkmcnt(2)
	v_lshlrev_b32_e32 v133, 16, v133
	v_add_f32_e32 v2, 1.0, v2
	v_rcp_f32_e32 v2, v2
	v_exp_f32_e32 v3, v3
	v_mul_f32_e32 v133, 0xbfb8aa3b, v133
	s_waitcnt lgkmcnt(1)
	v_lshlrev_b32_e32 v134, 16, v134
	v_fma_f32 v135, v126, v2, v160
	v_exp_f32_e32 v133, v133
	v_mul_f32_e32 v134, 0xbfb8aa3b, v134
	v_log_f32_e32 v136, v135
	v_exp_f32_e32 v135, v134
	v_add_f32_e32 v3, 1.0, v3
	v_rcp_f32_e32 v3, v3
	v_add_f32_e32 v133, 1.0, v133
	v_rcp_f32_e32 v134, v133
	v_add_f32_e32 v133, 1.0, v135
	v_rcp_f32_e32 v135, v133
	v_fma_f32 v137, v126, v3, v160
	v_log_f32_e32 v133, v137
	v_fma_f32 v137, v126, v134, v160
	v_log_f32_e32 v137, v137
	v_fma_f32 v173, v126, v135, v160
	v_log_f32_e32 v173, v173
	v_add_f32_e32 v187, 0, v136
	v_add_f32_e32 v186, v187, v133
	v_add_f32_e32 v185, v186, v137
	ds_read_u16 v183, v132 offset:32768
	ds_read_u16 v184, v132 offset:33024
	ds_read_u16 v182, v132 offset:33280
	v_add_f32_e32 v133, v185, v173
	ds_read_u16 v178, v132 offset:40960
	ds_read_u16 v173, v132 offset:45056
	ds_read_u16 v180, v132 offset:41216
	ds_read_u16 v174, v132 offset:45312
	ds_read_u16 v179, v132 offset:41472
	ds_read_u16 v175, v132 offset:45568
	ds_read_u16 v176, v132 offset:45824
	ds_read_u16 v181, v132 offset:41728
	ds_bpermute_b32 v137, v161, v133
	ds_bpermute_b32 v132, v162, v133
	v_mov_b32_e32 v188, 0
	s_waitcnt lgkmcnt(1)
	ds_bpermute_b32 v136, v162, v137
	s_and_saveexec_b64 s[56:57], s[4:5]
	s_cbranch_execz .LBB0_397
	v_cmp_lt_i32_e32 vcc, 1, v111
	v_mov_b32_e32 v188, v137
	s_and_saveexec_b64 s[58:59], vcc
	s_cbranch_execz .LBB0_396
	v_cmp_ne_u32_e32 vcc, 2, v111
	s_and_saveexec_b64 s[60:61], vcc
	s_xor_b64 s[60:61], exec, s[60:61]
	s_cbranch_execz .LBB0_393
	s_waitcnt lgkmcnt(1)
	v_add_f32_e32 v188, v137, v132
	s_waitcnt lgkmcnt(0)
	v_add_f32_e32 v188, v188, v136

; #define LAS __attribute__((address_space(3)))
; __device__ __forceinline__ unsigned cvtpk(float lo, float hi) { return pg8::cvt_pk_bf16(lo, hi); }
; __device__ __forceinline__ void scan_gate(const LAS unsigned char* raw, ScanSt& st, LAS unsigned char* buf, float lb, int w, int l16, int g) {
;     ...
;     for (int j = 0; j < 4; ++j) { const float bj = E + cs[j]; qd[j] = qv[j] * __builtin_amdgcn_exp2f(bj); fq_[j] = 1.0f - kk[j]; }
;     ib[3] = __builtin_amdgcn_exp2f(-(E + cs[3])); ib[2] = ib[3] * fq_[3]; ib[1] = ib[2] * fq_[2]; ib[0] = ib[1] * fq_[1];
; #pragma unroll
;     for (int j = 0; j < 4; ++j) { ki[j] = kk[j] * ib[j]; ks[j] = ki[j] * dec; }
;     const int colb = (16 * w + l16) * 2;
;     const unsigned q01 = cvtpk(qd[0], qd[1]), q23 = cvtpk(qd[2], qd[3]), k01 = cvtpk(ki[0], ki[1]), k23 = cvtpk(ki[2], ki[3]);
;     LAS unsigned char* qp = buf + SC_QD + (4 * g) * SC_RS + colb; LAS unsigned char* kp = buf + SC_KI + (4 * g) * SC_RS + colb;
;     *(LAS unsigned short*)(qp) = (unsigned short)(q01 & 0xffffu); *(LAS unsigned short*)(qp + SC_RS) = (unsigned short)(q01 >> 16);
;     *(LAS unsigned short*)(qp + 2 * SC_RS) = (unsigned short)(q23 & 0xffffu); *(LAS unsigned short*)(qp + 3 * SC_RS) = (unsigned short)(q23 >> 16);
;     *(LAS unsigned short*)(kp) = (unsigned short)(k01 & 0xffffu); *(LAS unsigned short*)(kp + SC_RS) = (unsigned short)(k01 >> 16);
;     *(LAS unsigned short*)(kp + 2 * SC_RS) = (unsigned short)(k23 & 0xffffu); *(LAS unsigned short*)(kp + 3 * SC_RS) = (unsigned short)(k23 >> 16);
;     *(LAS u32x2*)(buf + SC_KST + (16 * w + l16) * 32 + 8 * g) = (u32x2){cvtpk(ks[0], ks[1]), cvtpk(ks[2], ks[3])};
;     if (g == 0) *(LAS float*)(buf + SC_DEC + (16 * w + l16) * 4) = dec;
;     st.vf = __builtin_bit_cast(s16x4, (u32x2){rv[0] | (rv[1] << 16), rv[2] | (rv[3] << 16)});
; #pragma unroll
;     for (int j = 0; j < 4; ++j) st.gv[j] = bf2f(rg[j]);
; }
; __device__ __forceinline__ bf16x8 cat44(const s16x4 a, const s16x4 b) { return (bf16x8){a[0], a[1], a[2], a[3], b[0], b[1], b[2], b[3]}; }
; __device__ __forceinline__ void scan_mma(f32x4 (&St)[8], const ScanSt& st, f32x4& o, LAS unsigned char* buf, int w, int l16, int g) {
;     const LAS unsigned char* qp = buf + SC_QD + l16 * SC_RS + 8 * g; const LAS unsigned char* kp = buf + SC_KI + l16 * SC_RS + 8 * g;
;     bf16x8 qd[4], ki[4];
; #pragma unroll
.LBB0_409:
	s_or_b64 exec, exec, s[56:57]
	v_lshlrev_b32_e32 v66, 16, v59
	v_lshlrev_b32_e32 v59, 16, v0
	v_add_f32_e32 v0, v63, v64
	v_exp_f32_e32 v68, v0
	v_add_f32_e32 v0, v62, v64
	v_exp_f32_e32 v69, v0
	v_add_f32_e32 v0, v61, v64
	s_waitcnt lgkmcnt(0)
	v_pk_add_f32 v[56:57], v[52:53], v[56:57]
	v_exp_f32_e32 v52, v0
	v_add_f32_e32 v0, v53, v64
	v_exp_f32_e32 v53, v0
	v_lshlrev_b32_e32 v58, 16, v58
	v_pk_add_f32 v[54:55], v[54:55], 1.0 op_sel_hi:[1,0] neg_lo:[1,0] neg_hi:[1,0]
	v_pk_add_f32 v[2:3], v[2:3], 1.0 op_sel_hi:[1,0] neg_lo:[1,0] neg_hi:[1,0]
	v_pk_mul_f32 v[52:53], v[52:53], v[58:59]
	v_exp_f32_e64 v59, -v0
	v_pk_mul_f32 v[54:55], v[126:127], v[54:55]
	v_add_f32_e32 v0, v56, v57
	v_sub_f32_e32 v58, 1.0, v55
	v_pk_mul_f32 v[2:3], v[126:127], v[2:3]
	v_sub_f32_e32 v63, 1.0, v54
	v_exp_f32_e32 v0, v0
	v_mul_f32_e32 v58, v58, v59
	v_sub_f32_e32 v62, 1.0, v3
	v_mul_f32_e32 v57, v63, v58
	v_lshlrev_b32_e32 v67, 16, v60
	v_mul_f32_e32 v56, v62, v57
	v_pk_mul_f32 v[60:61], v[68:69], v[66:67]
	v_pk_mul_f32 v[2:3], v[2:3], v[56:57]
	v_pk_mul_f32 v[54:55], v[54:55], v[58:59]
	v_pk_mul_f32 v[56:57], v[0:1], v[2:3] op_sel_hi:[0,1]
	v_pk_mul_f32 v[58:59], v[0:1], v[54:55] op_sel_hi:[0,1]
	v_cvt_pk_bf16_f32 v60, v60, v61
	v_cvt_pk_bf16_f32 v52, v52, v53
	v_cvt_pk_bf16_f32 v2, v2, v3
	v_cvt_pk_bf16_f32 v3, v54, v55
	v_add_u32_e32 v53, v149, v143
	ds_write_b16 v53, v60 offset:16384
	ds_write_b16_d16_hi v53, v60 offset:16656
	ds_write_b16 v53, v52 offset:16928
	ds_write_b16_d16_hi v53, v52 offset:17200
	ds_write_b16 v53, v2 offset:20736
	ds_write_b16_d16_hi v53, v2 offset:21008
	ds_write_b16 v53, v3 offset:21280
	ds_write_b16_d16_hi v53, v3 offset:21552
	v_cvt_pk_bf16_f32 v2, v56, v57
	v_cvt_pk_bf16_f32 v3, v58, v59
	ds_write_b64 v164, v[2:3] offset:25088
	s_and_saveexec_b64 s[56:57], s[0:1]
	ds_write_b32 v155, v0 offset:29184
	s_or_b64 exec, exec, s[56:57]
	ds_read2_b64 v[52:55], v177 offset0:32 offset1:36
	ds_read2_b64 v[56:59], v156 offset1:4
	ds_read2_b64 v[60:63], v177 offset0:40 offset1:44
	ds_read2_b64 v[64:67], v156 offset0:8 offset1:12
	ds_read2_b64 v[68:71], v177 offset0:48 offset1:52
	v_mov_b32_e32 v0, s43
	s_waitcnt lgkmcnt(3)
	v_mfma_f32_16x16x32_bf16 v[52:55], v[52:55], v[56:59], 0
	s_waitcnt lgkmcnt(1)
	v_mfma_f32_16x16x32_bf16 v[52:55], v[60:63], v[64:67], v[52:55]
	ds_read2_b64 v[60:63], v156 offset0:16 offset1:20
	ds_read2_b64 v[72:75], v156 offset0:24 offset1:28
	ds_read2_b64 v[76:79], v177 offset0:56 offset1:60
	ds_read2st64_b64 v[80:83], v157 offset0:17 offset1:18
	s_waitcnt lgkmcnt(3)
	v_mfma_f32_16x16x32_bf16 v[52:55], v[68:71], v[60:63], v[52:55]
	ds_read_b128 v[68:71], v148 offset:12800
	v_mfma_f32_16x16x32_bf16 v[56:59], v[56:59], v[96:99], 0
	s_waitcnt lgkmcnt(2)
	v_mfma_f32_16x16x32_bf16 v[52:55], v[76:79], v[72:75], v[52:55]
	v_mfma_f32_16x16x32_bf16 v[56:59], v[64:67], v[92:95], v[56:59]
	ds_read_b128 v[64:67], v148 offset:12864
	s_nop 5
	v_cndmask_b32_e64 v0, v52, v0, s[6:7]
	v_cndmask_b32_e64 v2, 0, v53, s[8:9]
	v_cndmask_b32_e64 v3, v54, 0, s[10:11]
	v_cndmask_b32_e64 v53, v55, 0, s[12:13]
	v_cndmask_b32_e64 v0, v0, v52, s[8:9]
	v_cvt_pk_bf16_f32 v3, v3, v53
	v_mfma_f32_16x16x32_bf16 v[52:55], v[60:63], v[88:91], v[56:59]
	v_cvt_pk_bf16_f32 v2, v0, v2
	s_waitcnt lgkmcnt(0)
	v_pk_mul_f32 v[30:31], v[30:31], v[66:67]
	v_pk_mul_f32 v[28:29], v[28:29], v[64:65]
	v_mfma_f32_16x16x32_bf16 v[52:55], v[72:75], v[84:87], v[52:55]
	v_mul_f32_e64 v22, v22, v70
	v_mul_f32_e64 v23, v23, v71
	v_pk_mul_f32 v[20:21], v[20:21], v[68:69]
	ds_read_b128 v[56:59], v148 offset:12928
	ds_read_b128 v[60:63], v148 offset:12992
	ds_read2st64_b64 v[68:71], v157 offset0:19 offset1:20
	v_mfma_f32_16x16x16_bf16 v[64:67], v[82:83], v[130:131], v[28:31]
	s_waitcnt lgkmcnt(1)
	v_pk_mul_f32 v[34:35], v[34:35], v[62:63]
	s_nop 0
	ds_read2st64_b64 v[28:31], v157 offset0:21 offset1:22
	v_mfma_f32_16x16x16_bf16 v[100:103], v[2:3], v[130:131], v[52:55]
	v_mul_f32_e64 v32, v32, v60
	v_mul_f32_e64 v33, v33, v61
	ds_read_b128 v[60:63], v148 offset:13120
	v_pk_mul_f32 v[26:27], v[26:27], v[58:59]
	v_mfma_f32_16x16x16_bf16 v[52:55], v[80:81], v[130:131], v[20:23]
	v_mul_f32_e64 v24, v24, v56
	v_mul_f32_e64 v25, v25, v57
	s_nop 0
	ds_read_b128 v[20:23], v148 offset:13056
	s_waitcnt lgkmcnt(3)
	v_mfma_f32_16x16x16_bf16 v[56:59], v[68:69], v[130:131], v[24:27]
	s_waitcnt lgkmcnt(0)
	v_pk_mul_f32 v[22:23], v[38:39], v[22:23]
	v_pk_mul_f32 v[20:21], v[36:37], v[20:21]
	ds_read2st64_b64 v[36:39], v157 offset0:23 offset1:24
	v_pk_mul_f32 v[26:27], v[42:43], v[62:63]
	v_mfma_f32_16x16x16_bf16 v[72:75], v[28:29], v[130:131], v[20:23]
	v_mul_f32_e64 v24, v40, v60
	v_mul_f32_e64 v25, v41, v61
	s_waitcnt lgkmcnt(1)
	v_mfma_f32_16x16x16_bf16 v[60:63], v[70:71], v[130:131], v[32:35]
	s_nop 1
	ds_read_b128 v[32:35], v148 offset:13184
	ds_read_b128 v[40:43], v148 offset:13248
	s_waitcnt lgkmcnt(1)
	v_pk_mul_f32 v[22:23], v[46:47], v[34:35]
	v_mfma_f32_16x16x16_bf16 v[68:71], v[30:31], v[130:131], v[24:27]
	s_nop 2
	v_pk_mul_f32 v[20:21], v[44:45], v[32:33]
	s_waitcnt lgkmcnt(0)
	s_nop 0
	v_mfma_f32_16x16x16_bf16 v[76:79], v[36:37], v[130:131], v[20:23]
	v_mul_f32_e64 v28, v50, v42
	v_mul_f32_e64 v29, v51, v43
	v_pk_mul_f32 v[26:27], v[48:49], v[40:41]
	s_waitcnt lgkmcnt(0)
	s_nop 0
	v_mfma_f32_16x16x16_bf16 v[80:83], v[38:39], v[130:131], v[26:29]
	v_pk_mul_f32 v[20:21], v[100:101], v[100:101]
	v_pk_mul_f32 v[22:23], v[102:103], v[102:103]
	s_nop 1
	v_add_f32_dpp v20, v20, v20 row_ror:1 row_mask:0xf bank_mask:0xf
	v_add_f32_dpp v21, v21, v21 row_ror:1 row_mask:0xf bank_mask:0xf
	v_add_f32_dpp v22, v22, v22 row_ror:1 row_mask:0xf bank_mask:0xf
	v_add_f32_dpp v23, v23, v23 row_ror:1 row_mask:0xf bank_mask:0xf
	v_add_f32_dpp v20, v20, v20 row_ror:2 row_mask:0xf bank_mask:0xf
	v_add_f32_dpp v21, v21, v21 row_ror:2 row_mask:0xf bank_mask:0xf
	v_add_f32_dpp v22, v22, v22 row_ror:2 row_mask:0xf bank_mask:0xf
	v_add_f32_dpp v23, v23, v23 row_ror:2 row_mask:0xf bank_mask:0xf
	v_add_f32_dpp v20, v20, v20 row_ror:4 row_mask:0xf bank_mask:0xf
	v_add_f32_dpp v21, v21, v21 row_ror:4 row_mask:0xf bank_mask:0xf
	v_add_f32_dpp v22, v22, v22 row_ror:4 row_mask:0xf bank_mask:0xf
	v_add_f32_dpp v23, v23, v23 row_ror:4 row_mask:0xf bank_mask:0xf
	v_add_f32_dpp v20, v20, v20 row_ror:8 row_mask:0xf bank_mask:0xf
	v_add_f32_dpp v21, v21, v21 row_ror:8 row_mask:0xf bank_mask:0xf
	v_add_f32_dpp v22, v22, v22 row_ror:8 row_mask:0xf bank_mask:0xf
	v_add_f32_dpp v23, v23, v23 row_ror:8 row_mask:0xf bank_mask:0xf
	s_and_saveexec_b64 s[56:57], s[14:15]
	s_cbranch_execz .LBB0_413
	s_waitcnt lgkmcnt(0)
	v_add_u32_e32 v0, s3, v147
	ds_write_b128 v0, v[20:23] offset:13312

; #define LAS __attribute__((address_space(3)))
; __device__ __forceinline__ unsigned cvtpk(float lo, float hi) { return pg8::cvt_pk_bf16(lo, hi); }
; __device__ __forceinline__ bf16x8 cat44(const s16x4 a, const s16x4 b) { return (bf16x8){a[0], a[1], a[2], a[3], b[0], b[1], b[2], b[3]}; }
; __device__ __forceinline__ void scan_mma(f32x4 (&St)[8], const ScanSt& st, f32x4& o, LAS unsigned char* buf, int w, int l16, int g) {
;     const LAS unsigned char* qp = buf + SC_QD + l16 * SC_RS + 8 * g; const LAS unsigned char* kp = buf + SC_KI + l16 * SC_RS + 8 * g;
;     bf16x8 qd[4], ki[4];
; #pragma unroll
;     for (int ks = 0; ks < 4; ++ks) { qd[ks] = cat44(*(const LAS s16x4*)(qp + 64 * ks), *(const LAS s16x4*)(qp + 64 * ks + 32)); ki[ks] = cat44(*(const LAS s16x4*)(kp + 64 * ks), *(const LAS s16x4*)(kp + 64 * ks + 32)); }
;     f32x4 at = {0.f, 0.f, 0.f, 0.f};
; #pragma unroll
;     for (int ks = 0; ks < 4; ++ks) at = __builtin_amdgcn_mfma_f32_16x16x32_bf16(ki[ks], qd[ks], at, 0, 0, 0);
; #pragma unroll
;     for (int i = 0; i < 4; ++i) if (4 * g + i > l16) at[i] = 0.f;
;     const s16x4 pf = __builtin_bit_cast(s16x4, (u32x2){cvtpk(at[0], at[1]), cvtpk(at[2], at[3])});
;     f32x4 oo = {0.f, 0.f, 0.f, 0.f};
; #pragma unroll
;     for (int ks = 0; ks < 4; ++ks) { const f32x4 s0 = St[2 * ks], s1 = St[2 * ks + 1];
;         const bf16x8 sb = __builtin_bit_cast(bf16x8, (u32x4){cvtpk(s0[0], s0[1]), cvtpk(s0[2], s0[3]), cvtpk(s1[0], s1[1]), cvtpk(s1[2], s1[3])});
;         oo = __builtin_amdgcn_mfma_f32_16x16x32_bf16(qd[ks], sb, oo, 0, 0, 0); }
;     oo = __builtin_amdgcn_mfma_f32_16x16x16bf16_1k(pf, st.vf, oo, 0, 0, 0);
; #pragma unroll
;     for (int kt = 0; kt < 8; ++kt) { const s16x4 kst = *(const LAS s16x4*)(buf + SC_KST + (16 * kt + l16) * 32 + 8 * g); const f32x4 d4 = *(const LAS f32x4*)(buf + SC_DEC + (16 * kt + 4 * g) * 4);
;         St[kt] = __builtin_amdgcn_mfma_f32_16x16x16bf16_1k(kst, st.vf, St[kt] * d4, 0, 0, 0); }
;     o = oo;
;     f32x4 q2 = oo * oo;
; #pragma unroll
;     for (int off = 1; off < 16; off <<= 1) { q2[0] += __shfl_xor(q2[0], off); q2[1] += __shfl_xor(q2[1], off); q2[2] += __shfl_xor(q2[2], off); q2[3] += __shfl_xor(q2[3], off); }
;     if (l16 == 0) *(LAS f32x4*)(buf + SC_SSQ + (w * 16 + 4 * g) * 4) = q2;
; }
.LBB0_416:
	s_mov_b64 s[54:55], -1
	s_and_b64 vcc, exec, s[46:47]
	v_add_u32_e32 v177, 0, v147
	v_add_u32_e32 v178, 0x4000, v156
	v_add_u32_e32 v179, 0x5000, v156
	v_cvt_pk_bf16_f32 v96, v52, v53
	v_cvt_pk_bf16_f32 v97, v54, v55
	v_cvt_pk_bf16_f32 v98, v64, v65
	v_cvt_pk_bf16_f32 v99, v66, v67
	v_cvt_pk_bf16_f32 v92, v56, v57
	s_waitcnt lgkmcnt(4)
	v_cvt_pk_bf16_f32 v93, v58, v59
	v_cvt_pk_bf16_f32 v94, v60, v61
	v_cvt_pk_bf16_f32 v95, v62, v63
	v_cvt_pk_bf16_f32 v88, v72, v73
	v_cvt_pk_bf16_f32 v89, v74, v75
	v_cvt_pk_bf16_f32 v90, v68, v69
	v_cvt_pk_bf16_f32 v91, v70, v71
	v_cvt_pk_bf16_f32 v84, v76, v77
	v_cvt_pk_bf16_f32 v85, v78, v79
	v_cvt_pk_bf16_f32 v86, v80, v81
	v_cvt_pk_bf16_f32 v87, v82, v83
	s_cbranch_vccz .LBB0_430
	s_waitcnt lgkmcnt(4)
	ds_read2_b64 v[20:23], v179 offset0:32 offset1:36
	s_waitcnt lgkmcnt(3)
	ds_read2_b64 v[24:27], v178 offset1:4
	ds_read2_b64 v[28:31], v179 offset0:40 offset1:44
	ds_read2_b64 v[32:35], v178 offset0:8 offset1:12
	ds_read2_b64 v[36:39], v179 offset0:48 offset1:52
	v_mov_b32_e32 v0, s43
	s_waitcnt lgkmcnt(3)
	v_mfma_f32_16x16x32_bf16 v[20:23], v[20:23], v[24:27], 0
	s_waitcnt lgkmcnt(1)
	v_mfma_f32_16x16x32_bf16 v[20:23], v[28:31], v[32:35], v[20:23]
	ds_read2_b64 v[28:31], v178 offset0:16 offset1:20
	ds_read2_b64 v[40:43], v178 offset0:24 offset1:28
	ds_read2_b64 v[44:47], v179 offset0:56 offset1:60
	ds_read2st64_b64 v[48:51], v157 offset0:49 offset1:50
	s_waitcnt lgkmcnt(3)
	v_mfma_f32_16x16x32_bf16 v[20:23], v[36:39], v[28:31], v[20:23]
	ds_read_b128 v[36:39], v177 offset:29184
	v_mfma_f32_16x16x32_bf16 v[24:27], v[24:27], v[96:99], 0
	s_waitcnt lgkmcnt(2)
	v_mfma_f32_16x16x32_bf16 v[20:23], v[44:47], v[40:43], v[20:23]
	v_mfma_f32_16x16x32_bf16 v[24:27], v[32:35], v[92:95], v[24:27]
	ds_read_b128 v[32:35], v177 offset:29248
	s_nop 5
	v_cndmask_b32_e64 v0, v20, v0, s[6:7]
	v_cndmask_b32_e64 v44, 0, v21, s[8:9]
	v_cndmask_b32_e64 v21, v22, 0, s[10:11]
	v_cndmask_b32_e64 v22, v23, 0, s[12:13]
	v_cndmask_b32_e64 v0, v0, v20, s[8:9]
	v_cvt_pk_bf16_f32 v45, v21, v22
	v_mfma_f32_16x16x32_bf16 v[20:23], v[28:31], v[88:91], v[24:27]
	v_cvt_pk_bf16_f32 v44, v0, v44
	ds_read_b128 v[28:31], v177 offset:29312
	s_waitcnt lgkmcnt(2)
	v_pk_mul_f32 v[38:39], v[54:55], v[38:39]
	v_mfma_f32_16x16x32_bf16 v[20:23], v[40:43], v[84:87], v[20:23]
	v_mul_f32_e64 v36, v52, v36
	v_mul_f32_e64 v37, v53, v37
	s_waitcnt lgkmcnt(1)
	v_pk_mul_f32 v[24:25], v[64:65], v[32:33]
	v_pk_mul_f32 v[26:27], v[66:67], v[34:35]
	ds_read_b128 v[32:35], v177 offset:29376
	ds_read2st64_b64 v[40:43], v157 offset0:51 offset1:52
	v_mfma_f32_16x16x16_bf16 v[100:103], v[44:45], v[2:3], v[20:23]
	s_waitcnt lgkmcnt(2)
	v_pk_mul_f32 v[44:45], v[56:57], v[28:29]
	v_pk_mul_f32 v[46:47], v[58:59], v[30:31]
	ds_read_b128 v[130:133], v177 offset:29504
	v_mfma_f32_16x16x16_bf16 v[20:23], v[48:49], v[2:3], v[36:39]
	s_waitcnt lgkmcnt(2)
	v_pk_mul_f32 v[32:33], v[60:61], v[32:33]
	v_pk_mul_f32 v[34:35], v[62:63], v[34:35]
	v_mfma_f32_16x16x16_bf16 v[28:31], v[50:51], v[2:3], v[24:27]
	ds_read2st64_b64 v[48:51], v157 offset0:53 offset1:54
	ds_read2st64_b64 v[180:183], v157 offset0:55 offset1:56
	ds_read_b128 v[36:39], v177 offset:29440
	s_waitcnt lgkmcnt(4)
	v_mfma_f32_16x16x16_bf16 v[24:27], v[40:41], v[2:3], v[44:47]
	s_waitcnt lgkmcnt(0)
	v_pk_mul_f32 v[36:37], v[72:73], v[36:37]
	v_pk_mul_f32 v[38:39], v[74:75], v[38:39]
	v_pk_mul_f32 v[44:45], v[68:69], v[130:131]
	v_pk_mul_f32 v[46:47], v[70:71], v[132:133]
	v_mfma_f32_16x16x16_bf16 v[32:35], v[42:43], v[2:3], v[32:35]
	ds_read_b128 v[130:133], v177 offset:29568
	ds_read_b128 v[134:137], v177 offset:29632
	v_mfma_f32_16x16x16_bf16 v[36:39], v[48:49], v[2:3], v[36:39]
	s_waitcnt lgkmcnt(0)
	v_mfma_f32_16x16x16_bf16 v[40:43], v[50:51], v[2:3], v[44:47]
	s_nop 0
	v_pk_mul_f32 v[44:45], v[76:77], v[130:131]
	s_waitcnt lgkmcnt(0)
	v_pk_mul_f32 v[46:47], v[78:79], v[132:133]
	s_waitcnt lgkmcnt(0)
	v_pk_mul_f32 v[48:49], v[80:81], v[134:135]
	s_waitcnt lgkmcnt(0)
	v_pk_mul_f32 v[50:51], v[82:83], v[136:137]
	s_waitcnt lgkmcnt(0)
	v_mfma_f32_16x16x16_bf16 v[44:47], v[180:181], v[2:3], v[44:47]
	v_mfma_f32_16x16x16_bf16 v[48:51], v[182:183], v[2:3], v[48:51]
	v_pk_mul_f32 v[132:133], v[100:101], v[100:101]
	v_pk_mul_f32 v[134:135], v[102:103], v[102:103]
	s_nop 1
	v_add_f32_dpp v132, v132, v132 row_ror:1 row_mask:0xf bank_mask:0xf
	v_add_f32_dpp v133, v133, v133 row_ror:1 row_mask:0xf bank_mask:0xf
	v_add_f32_dpp v134, v134, v134 row_ror:1 row_mask:0xf bank_mask:0xf
	v_add_f32_dpp v135, v135, v135 row_ror:1 row_mask:0xf bank_mask:0xf
	v_add_f32_dpp v132, v132, v132 row_ror:2 row_mask:0xf bank_mask:0xf
	v_add_f32_dpp v133, v133, v133 row_ror:2 row_mask:0xf bank_mask:0xf
	v_add_f32_dpp v134, v134, v134 row_ror:2 row_mask:0xf bank_mask:0xf
	v_add_f32_dpp v135, v135, v135 row_ror:2 row_mask:0xf bank_mask:0xf
	v_add_f32_dpp v132, v132, v132 row_ror:4 row_mask:0xf bank_mask:0xf
	v_add_f32_dpp v133, v133, v133 row_ror:4 row_mask:0xf bank_mask:0xf
	v_add_f32_dpp v134, v134, v134 row_ror:4 row_mask:0xf bank_mask:0xf
	v_add_f32_dpp v135, v135, v135 row_ror:4 row_mask:0xf bank_mask:0xf
	v_add_f32_dpp v132, v132, v132 row_ror:8 row_mask:0xf bank_mask:0xf
	v_add_f32_dpp v133, v133, v133 row_ror:8 row_mask:0xf bank_mask:0xf
	v_add_f32_dpp v134, v134, v134 row_ror:8 row_mask:0xf bank_mask:0xf
	v_add_f32_dpp v135, v135, v135 row_ror:8 row_mask:0xf bank_mask:0xf
	s_and_saveexec_b64 s[54:55], s[14:15]
	s_cbranch_execz .LBB0_419
	s_waitcnt lgkmcnt(0)
	v_add_u32_e32 v0, s3, v147
	ds_write_b128 v0, v[132:135] offset:29696
; #define LAS __attribute__((address_space(3)))
; __device__ __forceinline__ float bf2f(unsigned h) { return __uint_as_float(h << 16); }
; __device__ __forceinline__ void scan_gate(const LAS unsigned char* raw, ScanSt& st, LAS unsigned char* buf, float lb, int w, int l16, int g) {
;     ...
;     const LAS unsigned char* e = raw + (4 * g) * 256 + ((2 * w + (l16 >> 3) + 2 * g) & 15) * 16 + (l16 & 7) * 2;
;     unsigned rq[4], rf[4], rv[4], rg[4];
; #pragma unroll
;     for (int j = 0; j < 4; ++j) { rq[j] = *(const LAS unsigned short*)(e + j * 256); rf[j] = *(const LAS unsigned short*)(e + 4096 + j * 256); rv[j] = *(const LAS unsigned short*)(e + 8192 + j * 256); rg[j] = *(const LAS unsigned short*)(e + 12288 + j * 256); }
;     float qv[4], kk[4], cs[4]; float run = 0.f;
; #pragma unroll
;     for (int j = 0; j < 4; ++j) { const float x = bf2f(rf[j]); const float sg = __builtin_amdgcn_rcpf(1.0f + __builtin_amdgcn_exp2f(-x * L2E));
;         const float f = lb + (1.0f - lb) * sg; kk[j] = (1.0f - lb) * (1.0f - sg); run += __builtin_amdgcn_logf(f); cs[j] = run; qv[j] = bf2f(rq[j]); }
;     const float T = run, t1 = __shfl_xor(T, 16), t2 = __shfl_xor(T, 32), t3 = __shfl_xor(t1, 32);
;     const float E = g == 0 ? 0.f : (g == 1 ? t1 : (g == 2 ? (t2 + t3) : (t1 + t2 + t3))), blast = (T + t1) + (t2 + t3);
.LBB0_419:
	s_or_b64 exec, exec, s[54:55]
	v_add_u32_e32 v0, s61, v139
	s_waitcnt lgkmcnt(1)
	v_add3_u32 v132, v0, v140, v141
	ds_read_u16 v130, v132 offset:36864
	ds_read_u16 v131, v132 offset:37120
	s_waitcnt lgkmcnt(3)
	ds_read_u16 v133, v132 offset:37376
	ds_read_u16 v134, v132 offset:37632
	ds_read_u16 v0, v132 offset:33536
	s_waitcnt lgkmcnt(4)
	v_lshlrev_b32_e32 v130, 16, v130
	v_mul_f32_e32 v130, 0xbfb8aa3b, v130
	v_exp_f32_e32 v130, v130
	s_waitcnt lgkmcnt(3)
	v_lshlrev_b32_e32 v131, 16, v131
	v_mul_f32_e32 v131, 0xbfb8aa3b, v131
	s_waitcnt lgkmcnt(2)
	v_lshlrev_b32_e32 v133, 16, v133
	v_add_f32_e32 v130, 1.0, v130
	v_rcp_f32_e32 v130, v130
	v_exp_f32_e32 v131, v131
	v_mul_f32_e32 v133, 0xbfb8aa3b, v133
	s_waitcnt lgkmcnt(1)
	v_lshlrev_b32_e32 v134, 16, v134
	v_fma_f32 v135, v126, v130, v160
	v_exp_f32_e32 v133, v133
	v_mul_f32_e32 v134, 0xbfb8aa3b, v134
	v_log_f32_e32 v136, v135
	v_exp_f32_e32 v135, v134
	v_add_f32_e32 v131, 1.0, v131
	v_rcp_f32_e32 v131, v131
	v_add_f32_e32 v133, 1.0, v133
	v_rcp_f32_e32 v134, v133
	v_add_f32_e32 v133, 1.0, v135
	v_rcp_f32_e32 v135, v133
	v_fma_f32 v137, v126, v131, v160
	v_log_f32_e32 v133, v137
	v_fma_f32 v137, v126, v134, v160
	v_log_f32_e32 v137, v137
	v_fma_f32 v169, v126, v135, v160
	v_log_f32_e32 v169, v169
	v_add_f32_e32 v189, 0, v136
	v_add_f32_e32 v188, v189, v133
	v_add_f32_e32 v187, v188, v137
	ds_read_u16 v185, v132 offset:32768
	ds_read_u16 v186, v132 offset:33024
	ds_read_u16 v184, v132 offset:33280
	v_add_f32_e32 v133, v187, v169
	ds_read_u16 v180, v132 offset:40960
	ds_read_u16 v169, v132 offset:45056
	ds_read_u16 v182, v132 offset:41216
	ds_read_u16 v170, v132 offset:45312
	ds_read_u16 v181, v132 offset:41472
	ds_read_u16 v171, v132 offset:45568
	ds_read_u16 v172, v132 offset:45824
	ds_read_u16 v183, v132 offset:41728
	ds_bpermute_b32 v137, v161, v133
	ds_bpermute_b32 v132, v162, v133
	v_mov_b32_e32 v190, 0
	s_waitcnt lgkmcnt(1)
	ds_bpermute_b32 v136, v162, v137
	s_and_saveexec_b64 s[54:55], s[4:5]
	s_cbranch_execz .LBB0_427
	v_cmp_lt_i32_e32 vcc, 1, v111
	v_mov_b32_e32 v190, v137
	s_and_saveexec_b64 s[56:57], vcc
	s_cbranch_execz .LBB0_426
	v_cmp_ne_u32_e32 vcc, 2, v111
	s_and_saveexec_b64 s[58:59], vcc
	s_xor_b64 s[58:59], exec, s[58:59]
	s_cbranch_execz .LBB0_423
	s_waitcnt lgkmcnt(1)
	v_add_f32_e32 v190, v137, v132
	s_waitcnt lgkmcnt(0)
	v_add_f32_e32 v190, v190, v136

; #define LAS __attribute__((address_space(3)))
; __device__ __forceinline__ unsigned cvtpk(float lo, float hi) { return pg8::cvt_pk_bf16(lo, hi); }
; __device__ __forceinline__ void scan_gate(const LAS unsigned char* raw, ScanSt& st, LAS unsigned char* buf, float lb, int w, int l16, int g) {
;     ...
;     for (int j = 0; j < 4; ++j) { const float bj = E + cs[j]; qd[j] = qv[j] * __builtin_amdgcn_exp2f(bj); fq_[j] = 1.0f - kk[j]; }
;     ib[3] = __builtin_amdgcn_exp2f(-(E + cs[3])); ib[2] = ib[3] * fq_[3]; ib[1] = ib[2] * fq_[2]; ib[0] = ib[1] * fq_[1];
; #pragma unroll
;     for (int j = 0; j < 4; ++j) { ki[j] = kk[j] * ib[j]; ks[j] = ki[j] * dec; }
;     const int colb = (16 * w + l16) * 2;
;     const unsigned q01 = cvtpk(qd[0], qd[1]), q23 = cvtpk(qd[2], qd[3]), k01 = cvtpk(ki[0], ki[1]), k23 = cvtpk(ki[2], ki[3]);
;     LAS unsigned char* qp = buf + SC_QD + (4 * g) * SC_RS + colb; LAS unsigned char* kp = buf + SC_KI + (4 * g) * SC_RS + colb;
;     *(LAS unsigned short*)(qp) = (unsigned short)(q01 & 0xffffu); *(LAS unsigned short*)(qp + SC_RS) = (unsigned short)(q01 >> 16);
;     *(LAS unsigned short*)(qp + 2 * SC_RS) = (unsigned short)(q23 & 0xffffu); *(LAS unsigned short*)(qp + 3 * SC_RS) = (unsigned short)(q23 >> 16);
;     *(LAS unsigned short*)(kp) = (unsigned short)(k01 & 0xffffu); *(LAS unsigned short*)(kp + SC_RS) = (unsigned short)(k01 >> 16);
;     *(LAS unsigned short*)(kp + 2 * SC_RS) = (unsigned short)(k23 & 0xffffu); *(LAS unsigned short*)(kp + 3 * SC_RS) = (unsigned short)(k23 >> 16);
;     *(LAS u32x2*)(buf + SC_KST + (16 * w + l16) * 32 + 8 * g) = (u32x2){cvtpk(ks[0], ks[1]), cvtpk(ks[2], ks[3])};
;     if (g == 0) *(LAS float*)(buf + SC_DEC + (16 * w + l16) * 4) = dec;
;     st.vf = __builtin_bit_cast(s16x4, (u32x2){rv[0] | (rv[1] << 16), rv[2] | (rv[3] << 16)});
; #pragma unroll
;     for (int j = 0; j < 4; ++j) st.gv[j] = bf2f(rg[j]);
; }
; __device__ __forceinline__ bf16x8 cat44(const s16x4 a, const s16x4 b) { return (bf16x8){a[0], a[1], a[2], a[3], b[0], b[1], b[2], b[3]}; }
; __device__ __forceinline__ void scan_mma(f32x4 (&St)[8], const ScanSt& st, f32x4& o, LAS unsigned char* buf, int w, int l16, int g) {
;     const LAS unsigned char* qp = buf + SC_QD + l16 * SC_RS + 8 * g; const LAS unsigned char* kp = buf + SC_KI + l16 * SC_RS + 8 * g;
;     bf16x8 qd[4], ki[4];
; #pragma unroll
.LBB0_439:
	s_or_b64 exec, exec, s[54:55]
	v_lshlrev_b32_e32 v36, 16, v29
	v_lshlrev_b32_e32 v29, 16, v0
	v_add_f32_e32 v0, v33, v34
	v_exp_f32_e32 v38, v0
	v_add_f32_e32 v0, v32, v34
	v_exp_f32_e32 v39, v0
	v_add_f32_e32 v0, v31, v34
	s_waitcnt lgkmcnt(0)
	v_pk_add_f32 v[26:27], v[22:23], v[26:27]
	v_exp_f32_e32 v22, v0
	v_add_f32_e32 v0, v23, v34
	v_exp_f32_e32 v23, v0
	v_lshlrev_b32_e32 v28, 16, v28
	v_pk_add_f32 v[24:25], v[24:25], 1.0 op_sel_hi:[1,0] neg_lo:[1,0] neg_hi:[1,0]
	v_pk_add_f32 v[20:21], v[20:21], 1.0 op_sel_hi:[1,0] neg_lo:[1,0] neg_hi:[1,0]
	v_pk_mul_f32 v[22:23], v[22:23], v[28:29]
	v_exp_f32_e64 v29, -v0
	v_pk_mul_f32 v[24:25], v[126:127], v[24:25]
	v_add_f32_e32 v0, v26, v27
	v_sub_f32_e32 v28, 1.0, v25
	v_pk_mul_f32 v[20:21], v[126:127], v[20:21]
	v_sub_f32_e32 v33, 1.0, v24
	v_exp_f32_e32 v0, v0
	v_mul_f32_e32 v28, v28, v29
	v_sub_f32_e32 v32, 1.0, v21
	v_mul_f32_e32 v27, v33, v28
	v_lshlrev_b32_e32 v37, 16, v30
	v_mul_f32_e32 v26, v32, v27
	v_pk_mul_f32 v[30:31], v[38:39], v[36:37]
	v_pk_mul_f32 v[20:21], v[20:21], v[26:27]
	v_pk_mul_f32 v[24:25], v[24:25], v[28:29]
	v_pk_mul_f32 v[26:27], v[0:1], v[20:21] op_sel_hi:[0,1]
	v_pk_mul_f32 v[28:29], v[0:1], v[24:25] op_sel_hi:[0,1]
	v_cvt_pk_bf16_f32 v30, v30, v31
	v_cvt_pk_bf16_f32 v20, v20, v21
	v_cvt_pk_bf16_f32 v21, v24, v25
	v_cvt_pk_bf16_f32 v22, v22, v23
	ds_write_b16 v163, v30
	ds_write_b16_d16_hi v163, v30 offset:272
	ds_write_b16 v163, v22 offset:544
	ds_write_b16_d16_hi v163, v22 offset:816
	ds_write_b16 v163, v20 offset:4352
	ds_write_b16_d16_hi v163, v20 offset:4624
	ds_write_b16 v163, v21 offset:4896
	ds_write_b16_d16_hi v163, v21 offset:5168
	v_cvt_pk_bf16_f32 v20, v26, v27
	v_cvt_pk_bf16_f32 v21, v28, v29
	ds_write_b64 v164, v[20:21] offset:8704
	s_and_saveexec_b64 s[54:55], s[0:1]
	ds_write_b32 v155, v0 offset:12800
	s_or_b64 exec, exec, s[54:55]
	ds_read2_b64 v[20:23], v179 offset0:32 offset1:36
	ds_read2_b64 v[24:27], v178 offset1:4
	ds_read2_b64 v[28:31], v179 offset0:40 offset1:44
	ds_read2_b64 v[32:35], v178 offset0:8 offset1:12
	ds_read2_b64 v[36:39], v179 offset0:48 offset1:52
	v_mov_b32_e32 v0, s43
	s_waitcnt lgkmcnt(3)
	v_mfma_f32_16x16x32_bf16 v[20:23], v[20:23], v[24:27], 0
	s_waitcnt lgkmcnt(1)
	v_mfma_f32_16x16x32_bf16 v[20:23], v[28:31], v[32:35], v[20:23]
	ds_read2_b64 v[28:31], v178 offset0:16 offset1:20
	ds_read2_b64 v[40:43], v178 offset0:24 offset1:28
	ds_read2_b64 v[44:47], v179 offset0:56 offset1:60
	ds_read2st64_b64 v[48:51], v157 offset0:49 offset1:50
	s_waitcnt lgkmcnt(3)
	v_mfma_f32_16x16x32_bf16 v[20:23], v[36:39], v[28:31], v[20:23]
	ds_read_b128 v[36:39], v177 offset:29184
	v_mfma_f32_16x16x32_bf16 v[24:27], v[24:27], v[96:99], 0
	s_waitcnt lgkmcnt(2)
	v_mfma_f32_16x16x32_bf16 v[20:23], v[44:47], v[40:43], v[20:23]
	v_mfma_f32_16x16x32_bf16 v[24:27], v[32:35], v[92:95], v[24:27]
	ds_read_b128 v[32:35], v177 offset:29248
	s_nop 5
	v_cndmask_b32_e64 v0, v20, v0, s[6:7]
	v_cndmask_b32_e64 v44, 0, v21, s[8:9]
	v_cndmask_b32_e64 v21, v22, 0, s[10:11]
	v_cndmask_b32_e64 v22, v23, 0, s[12:13]
	v_cndmask_b32_e64 v0, v0, v20, s[8:9]
	v_cvt_pk_bf16_f32 v45, v21, v22
	v_mfma_f32_16x16x32_bf16 v[20:23], v[28:31], v[88:91], v[24:27]
	v_cvt_pk_bf16_f32 v44, v0, v44
	ds_read_b128 v[28:31], v177 offset:29312
	s_waitcnt lgkmcnt(2)
	v_pk_mul_f32 v[38:39], v[54:55], v[38:39]
	v_mfma_f32_16x16x32_bf16 v[20:23], v[40:43], v[84:87], v[20:23]
	v_mul_f32_e64 v36, v52, v36
	v_mul_f32_e64 v37, v53, v37
	s_waitcnt lgkmcnt(1)
	v_pk_mul_f32 v[24:25], v[64:65], v[32:33]
	v_pk_mul_f32 v[26:27], v[66:67], v[34:35]
	ds_read_b128 v[32:35], v177 offset:29376
	ds_read2st64_b64 v[40:43], v157 offset0:51 offset1:52
	v_mfma_f32_16x16x16_bf16 v[100:103], v[44:45], v[2:3], v[20:23]
	s_waitcnt lgkmcnt(2)
	v_pk_mul_f32 v[44:45], v[56:57], v[28:29]
	v_pk_mul_f32 v[46:47], v[58:59], v[30:31]
	ds_read_b128 v[52:55], v177 offset:29504
	v_mfma_f32_16x16x16_bf16 v[20:23], v[48:49], v[2:3], v[36:39]
	s_waitcnt lgkmcnt(2)
	v_pk_mul_f32 v[32:33], v[60:61], v[32:33]
	v_pk_mul_f32 v[34:35], v[62:63], v[34:35]
	v_mfma_f32_16x16x16_bf16 v[28:31], v[50:51], v[2:3], v[24:27]
	ds_read2st64_b64 v[48:51], v157 offset0:53 offset1:54
	ds_read2st64_b64 v[58:61], v157 offset0:55 offset1:56
	ds_read_b128 v[36:39], v177 offset:29440
	s_waitcnt lgkmcnt(4)
	v_mfma_f32_16x16x16_bf16 v[24:27], v[40:41], v[2:3], v[44:47]
	s_waitcnt lgkmcnt(0)
	v_pk_mul_f32 v[36:37], v[72:73], v[36:37]
	v_pk_mul_f32 v[38:39], v[74:75], v[38:39]
	v_pk_mul_f32 v[44:45], v[68:69], v[52:53]
	v_pk_mul_f32 v[46:47], v[70:71], v[54:55]
	v_mfma_f32_16x16x16_bf16 v[32:35], v[42:43], v[2:3], v[32:35]
	ds_read_b128 v[52:55], v177 offset:29568
	ds_read_b128 v[62:65], v177 offset:29632
	v_mfma_f32_16x16x16_bf16 v[36:39], v[48:49], v[2:3], v[36:39]
	s_waitcnt lgkmcnt(0)
	v_mfma_f32_16x16x16_bf16 v[40:43], v[50:51], v[2:3], v[44:47]
	s_nop 0
	v_pk_mul_f32 v[44:45], v[76:77], v[52:53]
	s_waitcnt lgkmcnt(0)
	v_pk_mul_f32 v[46:47], v[78:79], v[54:55]
	s_waitcnt lgkmcnt(0)
	s_nop 0
	v_mfma_f32_16x16x16_bf16 v[44:47], v[58:59], v[2:3], v[44:47]
	s_waitcnt lgkmcnt(0)
	v_pk_mul_f32 v[50:51], v[82:83], v[64:65]
	v_pk_mul_f32 v[48:49], v[80:81], v[62:63]
	s_waitcnt lgkmcnt(0)
	s_nop 0
	v_mfma_f32_16x16x16_bf16 v[48:51], v[60:61], v[2:3], v[48:51]
	v_pk_mul_f32 v[54:55], v[100:101], v[100:101]
	v_pk_mul_f32 v[56:57], v[102:103], v[102:103]
	s_nop 1
	v_add_f32_dpp v54, v54, v54 row_ror:1 row_mask:0xf bank_mask:0xf
	v_add_f32_dpp v55, v55, v55 row_ror:1 row_mask:0xf bank_mask:0xf
	v_add_f32_dpp v56, v56, v56 row_ror:1 row_mask:0xf bank_mask:0xf
	v_add_f32_dpp v57, v57, v57 row_ror:1 row_mask:0xf bank_mask:0xf
	v_add_f32_dpp v54, v54, v54 row_ror:2 row_mask:0xf bank_mask:0xf
	v_add_f32_dpp v55, v55, v55 row_ror:2 row_mask:0xf bank_mask:0xf
	v_add_f32_dpp v56, v56, v56 row_ror:2 row_mask:0xf bank_mask:0xf
	v_add_f32_dpp v57, v57, v57 row_ror:2 row_mask:0xf bank_mask:0xf
	v_add_f32_dpp v54, v54, v54 row_ror:4 row_mask:0xf bank_mask:0xf
	v_add_f32_dpp v55, v55, v55 row_ror:4 row_mask:0xf bank_mask:0xf
	v_add_f32_dpp v56, v56, v56 row_ror:4 row_mask:0xf bank_mask:0xf
	v_add_f32_dpp v57, v57, v57 row_ror:4 row_mask:0xf bank_mask:0xf
	v_add_f32_dpp v54, v54, v54 row_ror:8 row_mask:0xf bank_mask:0xf
	v_add_f32_dpp v55, v55, v55 row_ror:8 row_mask:0xf bank_mask:0xf
	v_add_f32_dpp v56, v56, v56 row_ror:8 row_mask:0xf bank_mask:0xf
	v_add_f32_dpp v57, v57, v57 row_ror:8 row_mask:0xf bank_mask:0xf
	s_and_saveexec_b64 s[54:55], s[14:15]
	s_cbranch_execz .LBB0_443
	s_waitcnt lgkmcnt(0)
	v_add_u32_e32 v0, s3, v147
	ds_write_b128 v0, v[54:57] offset:29696
